# GLA sample new-state body rewritten by hand: state loads batched instead of one-per-store; prompt GLA epilogue loads hoisted
# speedup vs baseline: 1.0166x; 1.0166x over previous
; #define LAS __attribute__((address_space(3)))
; DI bf16_t f2bf(float a) { return (bf16_t)(pk2(a, 0.f) & 0xffffu); }
; DI float bf2f(bf16_t v) { return __uint_as_float(((unsigned)v) << 16); }
; #define LDS_WAIT() asm volatile("s_waitcnt lgkmcnt(0)" ::: "memory")
; template <bool SAMPLE>
; DI void gla_out(const Params& p, int item, int tbsel, LAS unsigned char* wl, int lane) {
;     ...
;     if (SAMPLE) {
;         LDS_WAIT();
;         float cum2 = 0.f;
; #pragma unroll
;         for (int t = 0; t < 16; ++t) {
;             cum2 += la[t * 256];
;             *(LAS bf16_t*)(Qs + lane * 144 + 2 * t) = f2bf(bf2f(kb[t * 256]) * __expf(tot - cum2));
;         }
;         ((LAS float*)Ks)[lane] = __expf(tot);
;         LDS_WAIT();
.LBB0_1008:
	s_or_b64 exec, exec, s[22:23]
	s_waitcnt lgkmcnt(0)
	global_load_dword v16, v[180:181], off
	global_load_ushort v17, v[182:183], off offset:512
	global_load_ushort v18, v[182:183], off
	global_load_ushort v19, v[182:183], off offset:1536
	global_load_ushort v20, v[182:183], off offset:1024
	global_load_ushort v21, v[182:183], off offset:2560
	global_load_ushort v22, v[182:183], off offset:2048
	global_load_dword v23, v[180:181], off offset:1024
	global_load_dword v24, v[180:181], off offset:2048
	global_load_dword v25, v[180:181], off offset:3072
	v_lshl_add_u64 v[0:1], v[180:181], 0, s[26:27]
	global_load_dword v26, v[0:1], off
	v_lshl_add_u64 v[0:1], v[180:181], 0, s[36:37]
	global_load_dword v27, v[0:1], off
	v_lshl_add_u64 v[0:1], v[180:181], 0, s[40:41]
	global_load_dword v28, v[0:1], off
	v_lshl_add_u64 v[0:1], v[180:181], 0, s[42:43]
	global_load_dword v29, v[0:1], off
	global_load_ushort v30, v[182:183], off offset:3072
	global_load_ushort v31, v[182:183], off offset:3584
	v_lshl_add_u64 v[0:1], v[180:181], 0, s[34:35]
	v_lshl_add_u64 v[4:5], v[180:181], 0, s[50:51]
	global_load_dword v32, v[0:1], off
	global_load_dword v33, v[4:5], off
	v_lshl_add_u64 v[0:1], v[182:183], 0, s[52:53]
	v_lshl_add_u64 v[2:3], v[182:183], 0, s[26:27]
	v_lshl_add_u64 v[6:7], v[180:181], 0, s[54:55]
	v_lshl_add_u64 v[8:9], v[182:183], 0, s[36:37]
	v_lshl_add_u64 v[4:5], v[182:183], 0, s[58:59]
	global_load_ushort v34, v[0:1], off
	global_load_dword v35, v[6:7], off
	global_load_ushort v36, v[4:5], off
	global_load_ushort v37, v[8:9], off
	global_load_ushort v38, v[2:3], off
	v_lshl_add_u64 v[0:1], v[180:181], 0, s[56:57]
	global_load_dword v39, v[0:1], off
	v_lshl_add_u64 v[0:1], v[180:181], 0, s[60:61]
	v_lshl_add_u64 v[12:13], v[180:181], 0, s[68:69]
	v_lshl_add_u64 v[14:15], v[182:183], 0, s[70:71]
	v_lshl_add_u64 v[2:3], v[182:183], 0, s[40:41]
	v_lshl_add_u64 v[4:5], v[180:181], 0, s[62:63]
	v_lshl_add_u64 v[6:7], v[182:183], 0, s[64:65]
	v_lshl_add_u64 v[8:9], v[180:181], 0, s[66:67]
	v_lshl_add_u64 v[10:11], v[182:183], 0, s[42:43]
	global_load_dword v40, v[0:1], off
	global_load_dword v41, v[4:5], off
	global_load_ushort v42, v[6:7], off
	global_load_dword v43, v[8:9], off
	s_nop 0
	global_load_dword v12, v[12:13], off
	s_nop 0
	global_load_ushort v13, v[14:15], off
	s_nop 0
	global_load_ushort v14, v[10:11], off
	global_load_ushort v15, v[2:3], off
	s_lshl_b64 s[22:23], s[28:29], 13
	v_add_u32_e32 v62, 0x4400, v185
	s_add_i32 s28, s28, s74
	s_cmpk_lt_i32 s28, 0x80
	s_waitcnt vmcnt(31)
	v_add_f32_e32 v6, 0, v16
	v_sub_f32_e32 v7, v197, v6
	v_mul_f32_e32 v7, 0x3fb8aa3b, v7
	s_waitcnt vmcnt(30)
	v_lshlrev_b32_e32 v1, 16, v17
	s_waitcnt vmcnt(29)
	v_lshlrev_b32_e32 v0, 16, v18
	s_waitcnt vmcnt(28)
	v_lshlrev_b32_e32 v3, 16, v19
	s_waitcnt vmcnt(27)
	v_lshlrev_b32_e32 v2, 16, v20
	s_waitcnt vmcnt(24)
	v_add_f32_e32 v6, v6, v23
	v_sub_f32_e32 v8, v197, v6
	s_waitcnt vmcnt(23)
	v_add_f32_e32 v9, v6, v24
	v_exp_f32_e32 v6, v7
	v_mul_f32_e32 v7, 0x3fb8aa3b, v8
	v_sub_f32_e32 v8, v197, v9
	s_waitcnt vmcnt(22)
	v_add_f32_e32 v9, v9, v25
	v_sub_f32_e32 v10, v197, v9
	s_waitcnt vmcnt(21)
	v_add_f32_e32 v9, v9, v26
	v_mul_f32_e32 v10, 0x3fb8aa3b, v10
	v_sub_f32_e32 v11, v197, v9
	s_waitcnt vmcnt(20)
	v_add_f32_e32 v16, v9, v27
	v_mul_f32_e32 v8, 0x3fb8aa3b, v8
	v_exp_f32_e32 v9, v10
	v_mul_f32_e32 v10, 0x3fb8aa3b, v11
	v_sub_f32_e32 v11, v197, v16
	v_exp_f32_e32 v7, v7
	v_exp_f32_e32 v8, v8
	v_mul_f32_e32 v11, 0x3fb8aa3b, v11
	v_exp_f32_e32 v10, v10
	v_exp_f32_e32 v11, v11
	s_waitcnt vmcnt(19)
	v_add_f32_e32 v16, v16, v28
	v_sub_f32_e32 v17, v197, v16
	s_waitcnt vmcnt(18)
	v_add_f32_e32 v16, v16, v29
	v_lshlrev_b32_e32 v5, 16, v21
	v_lshlrev_b32_e32 v4, 16, v22
	v_pk_mul_f32 v[0:1], v[6:7], v[0:1]
	v_sub_f32_e32 v7, v197, v16
	v_pk_mul_f32 v[2:3], v[8:9], v[2:3]
	v_mul_f32_e32 v6, 0x3fb8aa3b, v17
	v_cvt_pk_bf16_f32 v0, v0, v1
	v_cvt_pk_bf16_f32 v1, v2, v3
	v_pk_mul_f32 v[2:3], v[10:11], v[4:5]
	v_mul_f32_e32 v4, 0x3fb8aa3b, v7
	v_exp_f32_e32 v6, v6
	v_exp_f32_e32 v7, v4
	s_waitcnt vmcnt(16)
	v_lshlrev_b32_e32 v5, 16, v31
	v_lshlrev_b32_e32 v4, 16, v30
	v_cvt_pk_bf16_f32 v2, v2, v3
	v_pk_mul_f32 v[4:5], v[6:7], v[4:5]
	s_waitcnt vmcnt(2)
	v_lshlrev_b32_e32 v7, 16, v13
	v_cvt_pk_bf16_f32 v3, v4, v5
	v_add_f32_e32 v5, v16, v32
	v_add_f32_e32 v6, v5, v33
	v_sub_f32_e32 v4, v197, v5
	v_sub_f32_e32 v5, v197, v6
	v_mul_f32_e32 v4, 0x3fb8aa3b, v4
	v_mul_f32_e32 v5, 0x3fb8aa3b, v5
	ds_write_b128 v191, v[0:3] offset:8448
	v_add_f32_e32 v3, v6, v35
	v_exp_f32_e32 v4, v4
	v_exp_f32_e32 v5, v5
	v_add_f32_e32 v6, v3, v39
	v_sub_f32_e32 v2, v197, v3
	v_sub_f32_e32 v3, v197, v6
	v_mul_f32_e32 v2, 0x3fb8aa3b, v2
	v_mul_f32_e32 v3, 0x3fb8aa3b, v3
	v_lshlrev_b32_e32 v1, 16, v34
	v_lshlrev_b32_e32 v0, 16, v38
	v_exp_f32_e32 v2, v2
	v_exp_f32_e32 v3, v3
	v_pk_mul_f32 v[0:1], v[4:5], v[0:1]
	v_lshlrev_b32_e32 v5, 16, v36
	v_cvt_pk_bf16_f32 v0, v0, v1
	v_add_f32_e32 v1, v6, v40
	v_lshlrev_b32_e32 v4, 16, v37
	v_add_f32_e32 v6, v1, v41
	v_pk_mul_f32 v[2:3], v[2:3], v[4:5]
	v_sub_f32_e32 v4, v197, v1
	v_sub_f32_e32 v1, v197, v6
	v_mul_f32_e32 v4, 0x3fb8aa3b, v4
	v_mul_f32_e32 v1, 0x3fb8aa3b, v1
	v_exp_f32_e32 v4, v4
	v_exp_f32_e32 v5, v1
	v_cvt_pk_bf16_f32 v1, v2, v3
	v_lshlrev_b32_e32 v3, 16, v42
	s_waitcnt vmcnt(0)
	v_lshlrev_b32_e32 v2, 16, v15
	v_pk_mul_f32 v[2:3], v[4:5], v[2:3]
	v_add_f32_e32 v5, v6, v43
	v_sub_f32_e32 v4, v197, v5
	v_add_f32_e32 v5, v5, v12
	v_sub_f32_e32 v5, v197, v5
	v_mul_f32_e32 v4, 0x3fb8aa3b, v4
	v_mul_f32_e32 v5, 0x3fb8aa3b, v5
	v_exp_f32_e32 v4, v4
	v_exp_f32_e32 v5, v5
	v_lshlrev_b32_e32 v6, 16, v14
	v_cvt_pk_bf16_f32 v2, v2, v3
	v_lshl_add_u64 v[26:27], v[172:173], 0, v[88:89]
	v_pk_mul_f32 v[4:5], v[4:5], v[6:7]
	v_or_b32_e32 v20, s22, v144
	v_cvt_pk_bf16_f32 v3, v4, v5
	ds_write_b128 v191, v[0:3] offset:8464
	ds_write_b32 v194, v196 offset:17664
	s_waitcnt lgkmcnt(0)
; #define LAS __attribute__((address_space(3)))
; #define MFMA32(a, b, c) __builtin_amdgcn_mfma_f32_32x32x16_bf16((a), (b), (c), 0, 0, 0)
; template <bool SAMPLE>
; DI void gla_out(const Params& p, int item, int tbsel, LAS unsigned char* wl, int lane) {
;     ...
; #pragma unroll
;         for (int dkb = 0; dkb < 2; ++dkb) {
;             const bf16x8 ak = *(const LAS bf16x8*)(Qs + (32 * dkb + qi) * 144 + 8 * hh * 2);
; #pragma unroll
;             for (int dvb = 0; dvb < 4; ++dvb) {
;                 const bf16x8 bv = *(const bf16x8*)((const bf16_t*)(ws + OFF_VBTS) + (size_t)(sb * 512 + h * 128 + 32 * dvb + qi) * 16 + 8 * hh);
;                 f32x16 sl;
; #pragma unroll
;                 for (int r = 0; r < 16; ++r) sl[r] = 0.f;
;                 sl = MFMA32(ak, bv, sl);
; #pragma unroll
;                 for (int r = 0; r < 16; ++r) {
;                     const int dk = 32 * dkb + (r & 3) + 8 * (r >> 2) + 4 * hh;
;                     const size_t idx = (size_t)item * 8192 + (size_t)dk * 128 + 32 * dvb + qi;
;                     p.out[O_GLS + idx] = p.state_gla[idx] * ((const LAS float*)Ks)[dk] + sl[r];
;                 }
;             }
	v_bfe_u32 v10, v203, 5, 1
	v_lshlrev_b32_e32 v0, 2, v20
	v_lshl_add_u32 v0, v10, 11, v0
	v_add_u32_e32 v1, 0x1000, v0
	v_add_u32_e32 v2, 0x2000, v0
	v_add_u32_e32 v3, 0x3000, v0
	v_add_u32_e32 v4, 0x4000, v0
	v_add_u32_e32 v5, 0x5000, v0
	v_add_u32_e32 v6, 0x6000, v0
	v_add_u32_e32 v7, 0x7000, v0
	v_lshrrev_b32_e32 v9, 13, v20
	v_lshlrev_b32_e32 v9, 12, v9
	v_lshl_add_u32 v9, v144, 5, v9
	v_lshl_add_u32 v9, v10, 4, v9
	v_add_u32_e32 v8, 0xb8d0000, v9
	s_add_u32 s76, s24, 0x4940000
	s_addc_u32 s77, s25, 0
	global_load_dwordx4 v[12:15], v8, s[44:45]
	global_load_dwordx4 v[16:19], v8, s[44:45] offset:1024
	global_load_dwordx4 v[20:23], v8, s[44:45] offset:2048
	global_load_dwordx4 v[24:27], v8, s[44:45] offset:3072
	ds_read_b128 v[28:31], v186 offset:8448
	ds_read_b128 v[32:35], v186 offset:13056
	ds_read_b128 v[36:39], v185 offset:17664
	ds_read_b128 v[40:43], v185 offset:17696
	ds_read_b128 v[44:47], v185 offset:17728
	ds_read_b128 v[48:51], v185 offset:17760
	global_load_dword v204, v0, s[30:31]
	global_load_dword v205, v0, s[30:31] offset:512
	global_load_dword v206, v0, s[30:31] offset:1024
	global_load_dword v207, v0, s[30:31] offset:1536
	global_load_dword v208, v1, s[30:31]
	global_load_dword v209, v1, s[30:31] offset:512
	global_load_dword v210, v1, s[30:31] offset:1024
	global_load_dword v211, v1, s[30:31] offset:1536
	global_load_dword v212, v2, s[30:31]
	global_load_dword v213, v2, s[30:31] offset:512
	global_load_dword v214, v2, s[30:31] offset:1024
	global_load_dword v215, v2, s[30:31] offset:1536
	global_load_dword v216, v3, s[30:31]
	global_load_dword v217, v3, s[30:31] offset:512
	global_load_dword v218, v3, s[30:31] offset:1024
	global_load_dword v219, v3, s[30:31] offset:1536
	global_load_dword v220, v0, s[30:31] offset:128
	global_load_dword v221, v0, s[30:31] offset:640
	global_load_dword v222, v0, s[30:31] offset:1152
	global_load_dword v223, v0, s[30:31] offset:1664
	global_load_dword v224, v1, s[30:31] offset:128
	global_load_dword v225, v1, s[30:31] offset:640
	global_load_dword v226, v1, s[30:31] offset:1152
	global_load_dword v227, v1, s[30:31] offset:1664
	global_load_dword v228, v2, s[30:31] offset:128
	global_load_dword v229, v2, s[30:31] offset:640
	global_load_dword v230, v2, s[30:31] offset:1152
	global_load_dword v231, v2, s[30:31] offset:1664
	global_load_dword v232, v3, s[30:31] offset:128
	global_load_dword v233, v3, s[30:31] offset:640
	global_load_dword v234, v3, s[30:31] offset:1152
	global_load_dword v235, v3, s[30:31] offset:1664
	global_load_dword v236, v0, s[30:31] offset:256
	global_load_dword v237, v0, s[30:31] offset:768
	global_load_dword v238, v0, s[30:31] offset:1280
	global_load_dword v239, v0, s[30:31] offset:1792
	global_load_dword v240, v1, s[30:31] offset:256
	global_load_dword v241, v1, s[30:31] offset:768
	global_load_dword v242, v1, s[30:31] offset:1280
	global_load_dword v243, v1, s[30:31] offset:1792
	global_load_dword v244, v2, s[30:31] offset:256
	global_load_dword v245, v2, s[30:31] offset:768
	global_load_dword v246, v2, s[30:31] offset:1280
	global_load_dword v247, v2, s[30:31] offset:1792
	global_load_dword v248, v3, s[30:31] offset:256
	global_load_dword v249, v3, s[30:31] offset:768
	global_load_dword v250, v3, s[30:31] offset:1280
	global_load_dword v251, v3, s[30:31] offset:1792
	s_waitcnt vmcnt(0) lgkmcnt(0)
	global_load_dword v68, v0, s[30:31] offset:384
	global_load_dword v69, v0, s[30:31] offset:896
	global_load_dword v70, v0, s[30:31] offset:1408
	global_load_dword v71, v0, s[30:31] offset:1920
	global_load_dword v72, v1, s[30:31] offset:384
	global_load_dword v73, v1, s[30:31] offset:896
	global_load_dword v74, v1, s[30:31] offset:1408
	global_load_dword v75, v1, s[30:31] offset:1920
	global_load_dword v76, v2, s[30:31] offset:384
	global_load_dword v77, v2, s[30:31] offset:896
	global_load_dword v78, v2, s[30:31] offset:1408
	global_load_dword v79, v2, s[30:31] offset:1920
	global_load_dword v80, v3, s[30:31] offset:384
	global_load_dword v81, v3, s[30:31] offset:896
	global_load_dword v82, v3, s[30:31] offset:1408
	global_load_dword v83, v3, s[30:31] offset:1920
	v_mfma_f32_32x32x16_bf16 v[52:67], v[28:31], v[12:15], 0
	s_nop 11
	v_fma_f32 v52, v204, v36, v52
	v_fma_f32 v53, v205, v37, v53
	v_fma_f32 v54, v206, v38, v54
	v_fma_f32 v55, v207, v39, v55
	v_fma_f32 v56, v208, v40, v56
	v_fma_f32 v57, v209, v41, v57
	v_fma_f32 v58, v210, v42, v58
	v_fma_f32 v59, v211, v43, v59
	v_fma_f32 v60, v212, v44, v60
	v_fma_f32 v61, v213, v45, v61
	v_fma_f32 v62, v214, v46, v62
	v_fma_f32 v63, v215, v47, v63
	v_fma_f32 v64, v216, v48, v64
	v_fma_f32 v65, v217, v49, v65
	v_fma_f32 v66, v218, v50, v66
	v_fma_f32 v67, v219, v51, v67
	s_waitcnt vmcnt(40)
	global_store_dword v0, v52, s[76:77]
	global_store_dword v0, v53, s[76:77] offset:512
	global_store_dword v0, v54, s[76:77] offset:1024
	global_store_dword v0, v55, s[76:77] offset:1536
	global_store_dword v1, v56, s[76:77]
	global_store_dword v1, v57, s[76:77] offset:512
	global_store_dword v1, v58, s[76:77] offset:1024
	global_store_dword v1, v59, s[76:77] offset:1536
	global_store_dword v2, v60, s[76:77]
	global_store_dword v2, v61, s[76:77] offset:512
	global_store_dword v2, v62, s[76:77] offset:1024
	global_store_dword v2, v63, s[76:77] offset:1536
	global_store_dword v3, v64, s[76:77]
	global_store_dword v3, v65, s[76:77] offset:512
	global_store_dword v3, v66, s[76:77] offset:1024
	global_store_dword v3, v67, s[76:77] offset:1536
	v_mfma_f32_32x32x16_bf16 v[52:67], v[28:31], v[16:19], 0
	s_nop 11
	v_fma_f32 v52, v220, v36, v52
	v_fma_f32 v53, v221, v37, v53
	v_fma_f32 v54, v222, v38, v54
	v_fma_f32 v55, v223, v39, v55
	v_fma_f32 v56, v224, v40, v56
	v_fma_f32 v57, v225, v41, v57
	v_fma_f32 v58, v226, v42, v58
	v_fma_f32 v59, v227, v43, v59
	v_fma_f32 v60, v228, v44, v60
	v_fma_f32 v61, v229, v45, v61
	v_fma_f32 v62, v230, v46, v62
	v_fma_f32 v63, v231, v47, v63
	v_fma_f32 v64, v232, v48, v64
	v_fma_f32 v65, v233, v49, v65
	v_fma_f32 v66, v234, v50, v66
	v_fma_f32 v67, v235, v51, v67
	s_waitcnt vmcnt(40)
; #define LAS __attribute__((address_space(3)))
; #define MFMA32(a, b, c) __builtin_amdgcn_mfma_f32_32x32x16_bf16((a), (b), (c), 0, 0, 0)
; template <bool SAMPLE>
; DI void gla_out(const Params& p, int item, int tbsel, LAS unsigned char* wl, int lane) {
;     ...
; #pragma unroll
;         for (int dkb = 0; dkb < 2; ++dkb) {
;             const bf16x8 ak = *(const LAS bf16x8*)(Qs + (32 * dkb + qi) * 144 + 8 * hh * 2);
; #pragma unroll
;             for (int dvb = 0; dvb < 4; ++dvb) {
;                 const bf16x8 bv = *(const bf16x8*)((const bf16_t*)(ws + OFF_VBTS) + (size_t)(sb * 512 + h * 128 + 32 * dvb + qi) * 16 + 8 * hh);
;                 f32x16 sl;
; #pragma unroll
;                 for (int r = 0; r < 16; ++r) sl[r] = 0.f;
;                 sl = MFMA32(ak, bv, sl);
; #pragma unroll
;                 for (int r = 0; r < 16; ++r) {
;                     const int dk = 32 * dkb + (r & 3) + 8 * (r >> 2) + 4 * hh;
;                     const size_t idx = (size_t)item * 8192 + (size_t)dk * 128 + 32 * dvb + qi;
;                     p.out[O_GLS + idx] = p.state_gla[idx] * ((const LAS float*)Ks)[dk] + sl[r];
;                 }
;             }
	global_store_dword v0, v52, s[76:77] offset:128
	global_store_dword v0, v53, s[76:77] offset:640
	global_store_dword v0, v54, s[76:77] offset:1152
	global_store_dword v0, v55, s[76:77] offset:1664
	global_store_dword v1, v56, s[76:77] offset:128
	global_store_dword v1, v57, s[76:77] offset:640
	global_store_dword v1, v58, s[76:77] offset:1152
	global_store_dword v1, v59, s[76:77] offset:1664
	global_store_dword v2, v60, s[76:77] offset:128
	global_store_dword v2, v61, s[76:77] offset:640
	global_store_dword v2, v62, s[76:77] offset:1152
	global_store_dword v2, v63, s[76:77] offset:1664
	global_store_dword v3, v64, s[76:77] offset:128
	global_store_dword v3, v65, s[76:77] offset:640
	global_store_dword v3, v66, s[76:77] offset:1152
	global_store_dword v3, v67, s[76:77] offset:1664
	v_mfma_f32_32x32x16_bf16 v[52:67], v[28:31], v[20:23], 0
	s_nop 11
	v_fma_f32 v52, v236, v36, v52
	v_fma_f32 v53, v237, v37, v53
	v_fma_f32 v54, v238, v38, v54
	v_fma_f32 v55, v239, v39, v55
	v_fma_f32 v56, v240, v40, v56
	v_fma_f32 v57, v241, v41, v57
	v_fma_f32 v58, v242, v42, v58
	v_fma_f32 v59, v243, v43, v59
	v_fma_f32 v60, v244, v44, v60
	v_fma_f32 v61, v245, v45, v61
	v_fma_f32 v62, v246, v46, v62
	v_fma_f32 v63, v247, v47, v63
	v_fma_f32 v64, v248, v48, v64
	v_fma_f32 v65, v249, v49, v65
	v_fma_f32 v66, v250, v50, v66
	v_fma_f32 v67, v251, v51, v67
	s_waitcnt vmcnt(40)
	global_store_dword v0, v52, s[76:77] offset:256
	global_store_dword v0, v53, s[76:77] offset:768
	global_store_dword v0, v54, s[76:77] offset:1280
	global_store_dword v0, v55, s[76:77] offset:1792
	global_store_dword v1, v56, s[76:77] offset:256
	global_store_dword v1, v57, s[76:77] offset:768
	global_store_dword v1, v58, s[76:77] offset:1280
	global_store_dword v1, v59, s[76:77] offset:1792
	global_store_dword v2, v60, s[76:77] offset:256
	global_store_dword v2, v61, s[76:77] offset:768
	global_store_dword v2, v62, s[76:77] offset:1280
	global_store_dword v2, v63, s[76:77] offset:1792
	global_store_dword v3, v64, s[76:77] offset:256
	global_store_dword v3, v65, s[76:77] offset:768
	global_store_dword v3, v66, s[76:77] offset:1280
	global_store_dword v3, v67, s[76:77] offset:1792
	s_waitcnt vmcnt(48)
	v_mfma_f32_32x32x16_bf16 v[52:67], v[28:31], v[24:27], 0
	s_nop 11
	v_fma_f32 v52, v68, v36, v52
	v_fma_f32 v53, v69, v37, v53
	v_fma_f32 v54, v70, v38, v54
	v_fma_f32 v55, v71, v39, v55
	v_fma_f32 v56, v72, v40, v56
	v_fma_f32 v57, v73, v41, v57
	v_fma_f32 v58, v74, v42, v58
	v_fma_f32 v59, v75, v43, v59
	v_fma_f32 v60, v76, v44, v60
	v_fma_f32 v61, v77, v45, v61
	v_fma_f32 v62, v78, v46, v62
	v_fma_f32 v63, v79, v47, v63
	v_fma_f32 v64, v80, v48, v64
	v_fma_f32 v65, v81, v49, v65
	v_fma_f32 v66, v82, v50, v66
	v_fma_f32 v67, v83, v51, v67
	s_waitcnt vmcnt(40)
	global_store_dword v0, v52, s[76:77] offset:384
	global_store_dword v0, v53, s[76:77] offset:896
	global_store_dword v0, v54, s[76:77] offset:1408
	global_store_dword v0, v55, s[76:77] offset:1920
	global_store_dword v1, v56, s[76:77] offset:384
	global_store_dword v1, v57, s[76:77] offset:896
	global_store_dword v1, v58, s[76:77] offset:1408
	global_store_dword v1, v59, s[76:77] offset:1920
	global_store_dword v2, v60, s[76:77] offset:384
	global_store_dword v2, v61, s[76:77] offset:896
	global_store_dword v2, v62, s[76:77] offset:1408
	global_store_dword v2, v63, s[76:77] offset:1920
	global_store_dword v3, v64, s[76:77] offset:384
	global_store_dword v3, v65, s[76:77] offset:896
	global_store_dword v3, v66, s[76:77] offset:1408
	global_store_dword v3, v67, s[76:77] offset:1920
	s_waitcnt vmcnt(12)
	ds_read_b128 v[36:39], v185 offset:17792
	ds_read_b128 v[40:43], v185 offset:17824
	ds_read_b128 v[44:47], v185 offset:17856
	ds_read_b128 v[48:51], v185 offset:17888
	global_load_dword v204, v4, s[30:31]
	global_load_dword v205, v4, s[30:31] offset:512
	global_load_dword v206, v4, s[30:31] offset:1024
	global_load_dword v207, v4, s[30:31] offset:1536
	global_load_dword v208, v5, s[30:31]
	global_load_dword v209, v5, s[30:31] offset:512
	global_load_dword v210, v5, s[30:31] offset:1024
	global_load_dword v211, v5, s[30:31] offset:1536
	global_load_dword v212, v6, s[30:31]
	global_load_dword v213, v6, s[30:31] offset:512
	global_load_dword v214, v6, s[30:31] offset:1024
	global_load_dword v215, v6, s[30:31] offset:1536
	global_load_dword v216, v7, s[30:31]
	global_load_dword v217, v7, s[30:31] offset:512
	global_load_dword v218, v7, s[30:31] offset:1024
	global_load_dword v219, v7, s[30:31] offset:1536
	global_load_dword v220, v4, s[30:31] offset:128
	global_load_dword v221, v4, s[30:31] offset:640
	global_load_dword v222, v4, s[30:31] offset:1152
	global_load_dword v223, v4, s[30:31] offset:1664
	global_load_dword v224, v5, s[30:31] offset:128
	global_load_dword v225, v5, s[30:31] offset:640
	global_load_dword v226, v5, s[30:31] offset:1152
	global_load_dword v227, v5, s[30:31] offset:1664
	global_load_dword v228, v6, s[30:31] offset:128
	global_load_dword v229, v6, s[30:31] offset:640
	global_load_dword v230, v6, s[30:31] offset:1152
	global_load_dword v231, v6, s[30:31] offset:1664
	global_load_dword v232, v7, s[30:31] offset:128
	global_load_dword v233, v7, s[30:31] offset:640
	global_load_dword v234, v7, s[30:31] offset:1152
	global_load_dword v235, v7, s[30:31] offset:1664
	global_load_dword v236, v4, s[30:31] offset:256
	global_load_dword v237, v4, s[30:31] offset:768
	global_load_dword v238, v4, s[30:31] offset:1280
	global_load_dword v239, v4, s[30:31] offset:1792
	global_load_dword v240, v5, s[30:31] offset:256
	global_load_dword v241, v5, s[30:31] offset:768
	global_load_dword v242, v5, s[30:31] offset:1280
	global_load_dword v243, v5, s[30:31] offset:1792
	global_load_dword v244, v6, s[30:31] offset:256
	global_load_dword v245, v6, s[30:31] offset:768
	global_load_dword v246, v6, s[30:31] offset:1280
	global_load_dword v247, v6, s[30:31] offset:1792
	global_load_dword v248, v7, s[30:31] offset:256
	global_load_dword v249, v7, s[30:31] offset:768
	global_load_dword v250, v7, s[30:31] offset:1280
	global_load_dword v251, v7, s[30:31] offset:1792
	s_waitcnt vmcnt(0) lgkmcnt(0)
; #define LAS __attribute__((address_space(3)))
; #define MFMA32(a, b, c) __builtin_amdgcn_mfma_f32_32x32x16_bf16((a), (b), (c), 0, 0, 0)
; template <bool SAMPLE>
; DI void gla_out(const Params& p, int item, int tbsel, LAS unsigned char* wl, int lane) {
;     ...
; #pragma unroll
;         for (int dkb = 0; dkb < 2; ++dkb) {
;             const bf16x8 ak = *(const LAS bf16x8*)(Qs + (32 * dkb + qi) * 144 + 8 * hh * 2);
; #pragma unroll
;             for (int dvb = 0; dvb < 4; ++dvb) {
;                 const bf16x8 bv = *(const bf16x8*)((const bf16_t*)(ws + OFF_VBTS) + (size_t)(sb * 512 + h * 128 + 32 * dvb + qi) * 16 + 8 * hh);
;                 f32x16 sl;
; #pragma unroll
;                 for (int r = 0; r < 16; ++r) sl[r] = 0.f;
;                 sl = MFMA32(ak, bv, sl);
; #pragma unroll
;                 for (int r = 0; r < 16; ++r) {
;                     const int dk = 32 * dkb + (r & 3) + 8 * (r >> 2) + 4 * hh;
;                     const size_t idx = (size_t)item * 8192 + (size_t)dk * 128 + 32 * dvb + qi;
;                     p.out[O_GLS + idx] = p.state_gla[idx] * ((const LAS float*)Ks)[dk] + sl[r];
;                 }
;             }
; DI void p2_mixers(const Params& p, LAS unsigned char* lds) {
;     ...
;     { int s0 = gw - 1408; if (s0 < 0) s0 += NGW; for (int it = s0; it < 128; it += NGW) gla_out<true>(p, it, 0, wl, lane); }
	global_load_dword v68, v4, s[30:31] offset:384
	global_load_dword v69, v4, s[30:31] offset:896
	global_load_dword v70, v4, s[30:31] offset:1408
	global_load_dword v71, v4, s[30:31] offset:1920
	global_load_dword v72, v5, s[30:31] offset:384
	global_load_dword v73, v5, s[30:31] offset:896
	global_load_dword v74, v5, s[30:31] offset:1408
	global_load_dword v75, v5, s[30:31] offset:1920
	global_load_dword v76, v6, s[30:31] offset:384
	global_load_dword v77, v6, s[30:31] offset:896
	global_load_dword v78, v6, s[30:31] offset:1408
	global_load_dword v79, v6, s[30:31] offset:1920
	global_load_dword v80, v7, s[30:31] offset:384
	global_load_dword v81, v7, s[30:31] offset:896
	global_load_dword v82, v7, s[30:31] offset:1408
	global_load_dword v83, v7, s[30:31] offset:1920
	v_mfma_f32_32x32x16_bf16 v[52:67], v[32:35], v[12:15], 0
	s_nop 11
	v_fma_f32 v52, v204, v36, v52
	v_fma_f32 v53, v205, v37, v53
	v_fma_f32 v54, v206, v38, v54
	v_fma_f32 v55, v207, v39, v55
	v_fma_f32 v56, v208, v40, v56
	v_fma_f32 v57, v209, v41, v57
	v_fma_f32 v58, v210, v42, v58
	v_fma_f32 v59, v211, v43, v59
	v_fma_f32 v60, v212, v44, v60
	v_fma_f32 v61, v213, v45, v61
	v_fma_f32 v62, v214, v46, v62
	v_fma_f32 v63, v215, v47, v63
	v_fma_f32 v64, v216, v48, v64
	v_fma_f32 v65, v217, v49, v65
	v_fma_f32 v66, v218, v50, v66
	v_fma_f32 v67, v219, v51, v67
	s_waitcnt vmcnt(40)
	global_store_dword v4, v52, s[76:77]
	global_store_dword v4, v53, s[76:77] offset:512
	global_store_dword v4, v54, s[76:77] offset:1024
	global_store_dword v4, v55, s[76:77] offset:1536
	global_store_dword v5, v56, s[76:77]
	global_store_dword v5, v57, s[76:77] offset:512
	global_store_dword v5, v58, s[76:77] offset:1024
	global_store_dword v5, v59, s[76:77] offset:1536
	global_store_dword v6, v60, s[76:77]
	global_store_dword v6, v61, s[76:77] offset:512
	global_store_dword v6, v62, s[76:77] offset:1024
	global_store_dword v6, v63, s[76:77] offset:1536
	global_store_dword v7, v64, s[76:77]
	global_store_dword v7, v65, s[76:77] offset:512
	global_store_dword v7, v66, s[76:77] offset:1024
	global_store_dword v7, v67, s[76:77] offset:1536
	v_mfma_f32_32x32x16_bf16 v[52:67], v[32:35], v[16:19], 0
	s_nop 11
	v_fma_f32 v52, v220, v36, v52
	v_fma_f32 v53, v221, v37, v53
	v_fma_f32 v54, v222, v38, v54
	v_fma_f32 v55, v223, v39, v55
	v_fma_f32 v56, v224, v40, v56
	v_fma_f32 v57, v225, v41, v57
	v_fma_f32 v58, v226, v42, v58
	v_fma_f32 v59, v227, v43, v59
	v_fma_f32 v60, v228, v44, v60
	v_fma_f32 v61, v229, v45, v61
	v_fma_f32 v62, v230, v46, v62
	v_fma_f32 v63, v231, v47, v63
	v_fma_f32 v64, v232, v48, v64
	v_fma_f32 v65, v233, v49, v65
	v_fma_f32 v66, v234, v50, v66
	v_fma_f32 v67, v235, v51, v67
	s_waitcnt vmcnt(40)
	global_store_dword v4, v52, s[76:77] offset:128
	global_store_dword v4, v53, s[76:77] offset:640
	global_store_dword v4, v54, s[76:77] offset:1152
	global_store_dword v4, v55, s[76:77] offset:1664
	global_store_dword v5, v56, s[76:77] offset:128
	global_store_dword v5, v57, s[76:77] offset:640
	global_store_dword v5, v58, s[76:77] offset:1152
	global_store_dword v5, v59, s[76:77] offset:1664
	global_store_dword v6, v60, s[76:77] offset:128
	global_store_dword v6, v61, s[76:77] offset:640
	global_store_dword v6, v62, s[76:77] offset:1152
	global_store_dword v6, v63, s[76:77] offset:1664
	global_store_dword v7, v64, s[76:77] offset:128
	global_store_dword v7, v65, s[76:77] offset:640
	global_store_dword v7, v66, s[76:77] offset:1152
	global_store_dword v7, v67, s[76:77] offset:1664
	v_mfma_f32_32x32x16_bf16 v[52:67], v[32:35], v[20:23], 0
	s_nop 11
	v_fma_f32 v52, v236, v36, v52
	v_fma_f32 v53, v237, v37, v53
	v_fma_f32 v54, v238, v38, v54
	v_fma_f32 v55, v239, v39, v55
	v_fma_f32 v56, v240, v40, v56
	v_fma_f32 v57, v241, v41, v57
	v_fma_f32 v58, v242, v42, v58
	v_fma_f32 v59, v243, v43, v59
	v_fma_f32 v60, v244, v44, v60
	v_fma_f32 v61, v245, v45, v61
	v_fma_f32 v62, v246, v46, v62
	v_fma_f32 v63, v247, v47, v63
	v_fma_f32 v64, v248, v48, v64
	v_fma_f32 v65, v249, v49, v65
	v_fma_f32 v66, v250, v50, v66
	v_fma_f32 v67, v251, v51, v67
	s_waitcnt vmcnt(40)
	global_store_dword v4, v52, s[76:77] offset:256
	global_store_dword v4, v53, s[76:77] offset:768
	global_store_dword v4, v54, s[76:77] offset:1280
	global_store_dword v4, v55, s[76:77] offset:1792
	global_store_dword v5, v56, s[76:77] offset:256
	global_store_dword v5, v57, s[76:77] offset:768
	global_store_dword v5, v58, s[76:77] offset:1280
	global_store_dword v5, v59, s[76:77] offset:1792
	global_store_dword v6, v60, s[76:77] offset:256
	global_store_dword v6, v61, s[76:77] offset:768
	global_store_dword v6, v62, s[76:77] offset:1280
	global_store_dword v6, v63, s[76:77] offset:1792
	global_store_dword v7, v64, s[76:77] offset:256
	global_store_dword v7, v65, s[76:77] offset:768
	global_store_dword v7, v66, s[76:77] offset:1280
	global_store_dword v7, v67, s[76:77] offset:1792
	s_waitcnt vmcnt(48)
	v_mfma_f32_32x32x16_bf16 v[52:67], v[32:35], v[24:27], 0
	s_nop 11
	v_fma_f32 v52, v68, v36, v52
	v_fma_f32 v53, v69, v37, v53
	v_fma_f32 v54, v70, v38, v54
	v_fma_f32 v55, v71, v39, v55
	v_fma_f32 v56, v72, v40, v56
	v_fma_f32 v57, v73, v41, v57
	v_fma_f32 v58, v74, v42, v58
	v_fma_f32 v59, v75, v43, v59
	v_fma_f32 v60, v76, v44, v60
	v_fma_f32 v61, v77, v45, v61
	v_fma_f32 v62, v78, v46, v62
	v_fma_f32 v63, v79, v47, v63
	v_fma_f32 v64, v80, v48, v64
	v_fma_f32 v65, v81, v49, v65
	v_fma_f32 v66, v82, v50, v66
	v_fma_f32 v67, v83, v51, v67
	s_waitcnt vmcnt(40)
	global_store_dword v4, v52, s[76:77] offset:384
	global_store_dword v4, v53, s[76:77] offset:896
	global_store_dword v4, v54, s[76:77] offset:1408
	global_store_dword v4, v55, s[76:77] offset:1920
	global_store_dword v5, v56, s[76:77] offset:384
	global_store_dword v5, v57, s[76:77] offset:896
	global_store_dword v5, v58, s[76:77] offset:1408
	global_store_dword v5, v59, s[76:77] offset:1920
	global_store_dword v6, v60, s[76:77] offset:384
	global_store_dword v6, v61, s[76:77] offset:896
	global_store_dword v6, v62, s[76:77] offset:1408
	global_store_dword v6, v63, s[76:77] offset:1920
	global_store_dword v7, v64, s[76:77] offset:384
	global_store_dword v7, v65, s[76:77] offset:896
	global_store_dword v7, v66, s[76:77] offset:1408
	global_store_dword v7, v67, s[76:77] offset:1920
	s_cmpk_lt_i32 s28, 0x80
	s_waitcnt lgkmcnt(0)
	s_cbranch_scc0 .LBB0_1011

; DI unsigned pk2(float a, float b) { f32x2 v = {a, b}; bf2v r = __builtin_convertvector(v, bf2v); return __builtin_bit_cast(unsigned, r); }
; DI float bflo(unsigned w) { return __uint_as_float(w << 16); }
; DI float bfhi(unsigned w) { return __uint_as_float(w & 0xffff0000u); }
; template <bool SAMPLE>
; DI void gla_out(const Params& p, int item, int tbsel, LAS unsigned char* wl, int lane) {
;     ...
;         float ss = 0.f;
; #pragma unroll
;         for (int dvb = 0; dvb < 4; ++dvb)
; #pragma unroll
;             for (int r = 0; r < 16; ++r) ss += o[dvb][r] * o[dvb][r];
;         ss += __shfl_xor(ss, 32);
;         const float rstd = rsqrtf(ss * (1.f / 128.f) + EPS);
;         int lz = 0; asm volatile("" : "+v"(lz));
;         if (!SAMPLE || qi < 16) {
;             bf16_t* zr = (bf16_t*)(ws + OFF_ZB) + (size_t)(t0 + 32 * tb + qi) * 512 + h * 128 + 4 * hh;
; #pragma unroll
;             for (int dvb = 0; dvb < 4; ++dvb)
; #pragma unroll
;                 for (int g = 0; g < 4; ++g) {
;                     const int dv = 32 * dvb + 8 * g;
;                     const f32x4 gg = *(const f32x4*)(p.g_gla_out + dv + 4 * hh + lz);
;                     const u32x2 z = *(const u32x2*)(zr + dv); u32x2 w;
;                     w.x = pk2(o[dvb][4 * g] * rstd * gg[0] * bflo(z.x), o[dvb][4 * g + 1] * rstd * gg[1] * bfhi(z.x));
;                     w.y = pk2(o[dvb][4 * g + 2] * rstd * gg[2] * bflo(z.y), o[dvb][4 * g + 3] * rstd * gg[3] * bfhi(z.y));
;                     *(u32x2*)(zr + dv) = w;
;                 }
.LBB0_1130:
	v_or_b32_e32 v66, s58, v197
	v_ashrrev_i32_e32 v67, 31, v66
	s_and_b32 s38, s50, 3
	v_mov_b32_e32 v64, 0
	v_lshlrev_b64 v[66:67], 10, v[66:67]
	v_lshl_add_u64 v[68:69], s[52:53], 0, v[66:67]
	v_ashrrev_i32_e32 v65, 31, v64
	s_lshl_b32 s50, s38, 8
	v_lshl_add_u64 v[66:67], v[64:65], 2, v[184:185]
	v_lshl_add_u64 v[64:65], v[68:69], 0, s[50:51]
	v_lshl_add_u64 v[64:65], v[64:65], 0, v[178:179]
	global_load_dwordx2 v[132:133], v[64:65], off
	global_load_dwordx2 v[134:135], v[64:65], off offset:16
	global_load_dwordx2 v[136:137], v[64:65], off offset:32
	global_load_dwordx2 v[138:139], v[64:65], off offset:48
	global_load_dwordx2 v[140:141], v[64:65], off offset:64
	global_load_dwordx2 v[142:143], v[64:65], off offset:80
	global_load_dwordx2 v[144:145], v[64:65], off offset:96
	global_load_dwordx2 v[146:147], v[64:65], off offset:112
	global_load_dwordx2 v[148:149], v[64:65], off offset:128
	global_load_dwordx2 v[150:151], v[64:65], off offset:144
	global_load_dwordx2 v[152:153], v[64:65], off offset:160
	global_load_dwordx2 v[154:155], v[64:65], off offset:176
	global_load_dwordx2 v[156:157], v[64:65], off offset:192
	global_load_dwordx2 v[158:159], v[64:65], off offset:208
	global_load_dwordx2 v[160:161], v[64:65], off offset:224
	global_load_dwordx2 v[162:163], v[64:65], off offset:240
	global_load_dwordx4 v[204:207], v[66:67], off
	global_load_dwordx4 v[208:211], v[66:67], off offset:32
	global_load_dwordx4 v[212:215], v[66:67], off offset:64
	global_load_dwordx4 v[216:219], v[66:67], off offset:96
	global_load_dwordx4 v[220:223], v[66:67], off offset:128
	global_load_dwordx4 v[224:227], v[66:67], off offset:160
	global_load_dwordx4 v[228:231], v[66:67], off offset:192
	global_load_dwordx4 v[232:235], v[66:67], off offset:224
	global_load_dwordx4 v[236:239], v[66:67], off offset:256
	global_load_dwordx4 v[240:243], v[66:67], off offset:288
	global_load_dwordx4 v[244:247], v[66:67], off offset:320
	global_load_dwordx4 v[248:251], v[66:67], off offset:352
	global_load_dwordx4 v[116:119], v[66:67], off offset:384
	global_load_dwordx4 v[120:123], v[66:67], off offset:416
	global_load_dwordx4 v[124:127], v[66:67], off offset:448
	global_load_dwordx4 v[128:131], v[66:67], off offset:480
	v_mul_f32_e32 v84, v49, v49
	v_fmac_f32_e32 v84, v48, v48
	v_fmac_f32_e32 v84, v50, v50
	v_fmac_f32_e32 v84, v51, v51
	v_fmac_f32_e32 v84, v52, v52
	v_fmac_f32_e32 v84, v53, v53
	v_fmac_f32_e32 v84, v54, v54
	v_fmac_f32_e32 v84, v55, v55
	v_fmac_f32_e32 v84, v56, v56
	v_fmac_f32_e32 v84, v57, v57
	v_fmac_f32_e32 v84, v58, v58
	v_fmac_f32_e32 v84, v59, v59
	v_fmac_f32_e32 v84, v60, v60
	v_fmac_f32_e32 v84, v61, v61
	v_fmac_f32_e32 v84, v62, v62
	v_fmac_f32_e32 v84, v63, v63
	v_fmac_f32_e32 v84, v32, v32
	v_fmac_f32_e32 v84, v33, v33
	v_fmac_f32_e32 v84, v34, v34
	v_fmac_f32_e32 v84, v35, v35
	v_fmac_f32_e32 v84, v36, v36
	v_fmac_f32_e32 v84, v37, v37
	v_fmac_f32_e32 v84, v38, v38
	v_fmac_f32_e32 v84, v39, v39
	v_fmac_f32_e32 v84, v40, v40
	v_fmac_f32_e32 v84, v41, v41
	v_fmac_f32_e32 v84, v42, v42
	v_fmac_f32_e32 v84, v43, v43
	v_fmac_f32_e32 v84, v44, v44
	v_fmac_f32_e32 v84, v45, v45
	v_fmac_f32_e32 v84, v46, v46
	v_fmac_f32_e32 v84, v47, v47
	v_fmac_f32_e32 v84, v16, v16
	v_fmac_f32_e32 v84, v17, v17
	v_fmac_f32_e32 v84, v18, v18
	v_fmac_f32_e32 v84, v19, v19
	v_fmac_f32_e32 v84, v20, v20
	v_fmac_f32_e32 v84, v21, v21
	v_fmac_f32_e32 v84, v22, v22
	v_fmac_f32_e32 v84, v23, v23
	v_fmac_f32_e32 v84, v24, v24
	v_fmac_f32_e32 v84, v25, v25
	v_fmac_f32_e32 v84, v26, v26
	v_fmac_f32_e32 v84, v27, v27
	v_fmac_f32_e32 v84, v28, v28
	v_fmac_f32_e32 v84, v29, v29
	v_fmac_f32_e32 v84, v30, v30
	v_fmac_f32_e32 v84, v31, v31
	v_fmac_f32_e32 v84, v0, v0
	v_fmac_f32_e32 v84, v1, v1
	v_fmac_f32_e32 v84, v2, v2
	v_fmac_f32_e32 v84, v3, v3
	v_fmac_f32_e32 v84, v4, v4
	v_fmac_f32_e32 v84, v5, v5
	v_pk_mul_f32 v[82:83], v[6:7], v[6:7]
	v_pk_mul_f32 v[80:81], v[8:9], v[8:9]
	v_add_f32_e32 v82, v82, v84
	v_add_f32_e32 v82, v83, v82
	v_add_f32_e32 v80, v80, v82
	v_pk_mul_f32 v[78:79], v[10:11], v[10:11]
	v_add_f32_e32 v80, v81, v80
	v_add_f32_e32 v78, v78, v80
	v_pk_mul_f32 v[76:77], v[12:13], v[12:13]
	v_add_f32_e32 v78, v79, v78
	v_add_f32_e32 v76, v76, v78
	v_pk_mul_f32 v[68:69], v[14:15], v[14:15]
	v_add_f32_e32 v76, v77, v76
	v_add_f32_e32 v68, v68, v76
	v_cmp_lt_i32_e32 vcc, v188, v189
	v_add_f32_e32 v68, v69, v68
	s_nop 0
	v_cndmask_b32_e32 v69, v187, v188, vcc
	v_lshlrev_b32_e32 v69, 2, v69
	ds_bpermute_b32 v69, v69, v68
	s_waitcnt lgkmcnt(0)
	v_add_f32_e32 v68, v68, v69
	v_fmamk_f32 v68, v68, 0x3c000000, v196
	v_mul_f32_e32 v69, 0x4b800000, v68
	v_cmp_gt_f32_e32 vcc, s71, v68
	s_nop 1
	v_cndmask_b32_e32 v68, v68, v69, vcc
	v_rsq_f32_e32 v68, v68
	s_nop 0
	v_mul_f32_e32 v69, 0x45800000, v68
	v_cndmask_b32_e32 v68, v68, v69, vcc
	v_pk_mul_f32 v[48:49], v[48:49], v[68:69] op_sel_hi:[1,0]
	v_pk_mul_f32 v[50:51], v[50:51], v[68:69] op_sel_hi:[1,0]
	s_waitcnt vmcnt(15)
	v_lshlrev_b32_e32 v70, 16, v132
	v_and_b32_e32 v71, 0xffff0000, v132
	v_lshlrev_b32_e32 v72, 16, v133
	v_and_b32_e32 v73, 0xffff0000, v133
	v_pk_mul_f32 v[48:49], v[204:205], v[48:49]
	v_pk_mul_f32 v[50:51], v[206:207], v[50:51]
	v_pk_mul_f32 v[48:49], v[48:49], v[70:71]
	v_pk_mul_f32 v[50:51], v[50:51], v[72:73]
	v_cvt_pk_bf16_f32 v48, v48, v49
	v_cvt_pk_bf16_f32 v49, v50, v51
	global_store_dwordx2 v[64:65], v[48:49], off
	v_pk_mul_f32 v[52:53], v[52:53], v[68:69] op_sel_hi:[1,0]
	v_pk_mul_f32 v[54:55], v[54:55], v[68:69] op_sel_hi:[1,0]
	s_waitcnt vmcnt(15)
; DI unsigned pk2(float a, float b) { f32x2 v = {a, b}; bf2v r = __builtin_convertvector(v, bf2v); return __builtin_bit_cast(unsigned, r); }
; DI float bflo(unsigned w) { return __uint_as_float(w << 16); }
; DI float bfhi(unsigned w) { return __uint_as_float(w & 0xffff0000u); }
; template <bool SAMPLE>
; DI void gla_out(const Params& p, int item, int tbsel, LAS unsigned char* wl, int lane) {
;     ...
;         if (!SAMPLE || qi < 16) {
;             bf16_t* zr = (bf16_t*)(ws + OFF_ZB) + (size_t)(t0 + 32 * tb + qi) * 512 + h * 128 + 4 * hh;
; #pragma unroll
;             for (int dvb = 0; dvb < 4; ++dvb)
; #pragma unroll
;                 for (int g = 0; g < 4; ++g) {
;                     const int dv = 32 * dvb + 8 * g;
;                     const f32x4 gg = *(const f32x4*)(p.g_gla_out + dv + 4 * hh + lz);
;                     const u32x2 z = *(const u32x2*)(zr + dv); u32x2 w;
;                     w.x = pk2(o[dvb][4 * g] * rstd * gg[0] * bflo(z.x), o[dvb][4 * g + 1] * rstd * gg[1] * bfhi(z.x));
;                     w.y = pk2(o[dvb][4 * g + 2] * rstd * gg[2] * bflo(z.y), o[dvb][4 * g + 3] * rstd * gg[3] * bfhi(z.y));
;                     *(u32x2*)(zr + dv) = w;
;                 }
	v_lshlrev_b32_e32 v70, 16, v134
	v_and_b32_e32 v71, 0xffff0000, v134
	v_lshlrev_b32_e32 v72, 16, v135
	v_and_b32_e32 v73, 0xffff0000, v135
	v_pk_mul_f32 v[52:53], v[208:209], v[52:53]
	v_pk_mul_f32 v[54:55], v[210:211], v[54:55]
	v_pk_mul_f32 v[52:53], v[52:53], v[70:71]
	v_pk_mul_f32 v[54:55], v[54:55], v[72:73]
	v_cvt_pk_bf16_f32 v52, v52, v53
	v_cvt_pk_bf16_f32 v53, v54, v55
	global_store_dwordx2 v[64:65], v[52:53], off offset:16
	v_pk_mul_f32 v[56:57], v[56:57], v[68:69] op_sel_hi:[1,0]
	v_pk_mul_f32 v[58:59], v[58:59], v[68:69] op_sel_hi:[1,0]
	s_waitcnt vmcnt(15)
	v_lshlrev_b32_e32 v70, 16, v136
	v_and_b32_e32 v71, 0xffff0000, v136
	v_lshlrev_b32_e32 v72, 16, v137
	v_and_b32_e32 v73, 0xffff0000, v137
	v_pk_mul_f32 v[56:57], v[212:213], v[56:57]
	v_pk_mul_f32 v[58:59], v[214:215], v[58:59]
	v_pk_mul_f32 v[56:57], v[56:57], v[70:71]
	v_pk_mul_f32 v[58:59], v[58:59], v[72:73]
	v_cvt_pk_bf16_f32 v56, v56, v57
	v_cvt_pk_bf16_f32 v57, v58, v59
	global_store_dwordx2 v[64:65], v[56:57], off offset:32
	v_pk_mul_f32 v[60:61], v[60:61], v[68:69] op_sel_hi:[1,0]
	v_pk_mul_f32 v[62:63], v[62:63], v[68:69] op_sel_hi:[1,0]
	s_waitcnt vmcnt(15)
	v_lshlrev_b32_e32 v70, 16, v138
	v_and_b32_e32 v71, 0xffff0000, v138
	v_lshlrev_b32_e32 v72, 16, v139
	v_and_b32_e32 v73, 0xffff0000, v139
	v_pk_mul_f32 v[60:61], v[216:217], v[60:61]
	v_pk_mul_f32 v[62:63], v[218:219], v[62:63]
	v_pk_mul_f32 v[60:61], v[60:61], v[70:71]
	v_pk_mul_f32 v[62:63], v[62:63], v[72:73]
	v_cvt_pk_bf16_f32 v60, v60, v61
	v_cvt_pk_bf16_f32 v61, v62, v63
	global_store_dwordx2 v[64:65], v[60:61], off offset:48
	v_pk_mul_f32 v[32:33], v[32:33], v[68:69] op_sel_hi:[1,0]
	v_pk_mul_f32 v[34:35], v[34:35], v[68:69] op_sel_hi:[1,0]
	s_waitcnt vmcnt(15)
	v_lshlrev_b32_e32 v70, 16, v140
	v_and_b32_e32 v71, 0xffff0000, v140
	v_lshlrev_b32_e32 v72, 16, v141
	v_and_b32_e32 v73, 0xffff0000, v141
	v_pk_mul_f32 v[32:33], v[220:221], v[32:33]
	v_pk_mul_f32 v[34:35], v[222:223], v[34:35]
	v_pk_mul_f32 v[32:33], v[32:33], v[70:71]
	v_pk_mul_f32 v[34:35], v[34:35], v[72:73]
	v_cvt_pk_bf16_f32 v32, v32, v33
	v_cvt_pk_bf16_f32 v33, v34, v35
	global_store_dwordx2 v[64:65], v[32:33], off offset:64
	v_pk_mul_f32 v[36:37], v[36:37], v[68:69] op_sel_hi:[1,0]
	v_pk_mul_f32 v[38:39], v[38:39], v[68:69] op_sel_hi:[1,0]
	s_waitcnt vmcnt(15)
	v_lshlrev_b32_e32 v70, 16, v142
	v_and_b32_e32 v71, 0xffff0000, v142
	v_lshlrev_b32_e32 v72, 16, v143
	v_and_b32_e32 v73, 0xffff0000, v143
	v_pk_mul_f32 v[36:37], v[224:225], v[36:37]
	v_pk_mul_f32 v[38:39], v[226:227], v[38:39]
	v_pk_mul_f32 v[36:37], v[36:37], v[70:71]
	v_pk_mul_f32 v[38:39], v[38:39], v[72:73]
	v_cvt_pk_bf16_f32 v36, v36, v37
	v_cvt_pk_bf16_f32 v37, v38, v39
	global_store_dwordx2 v[64:65], v[36:37], off offset:80
	v_pk_mul_f32 v[40:41], v[40:41], v[68:69] op_sel_hi:[1,0]
	v_pk_mul_f32 v[42:43], v[42:43], v[68:69] op_sel_hi:[1,0]
	s_waitcnt vmcnt(15)
	v_lshlrev_b32_e32 v70, 16, v144
	v_and_b32_e32 v71, 0xffff0000, v144
	v_lshlrev_b32_e32 v72, 16, v145
	v_and_b32_e32 v73, 0xffff0000, v145
	v_pk_mul_f32 v[40:41], v[228:229], v[40:41]
	v_pk_mul_f32 v[42:43], v[230:231], v[42:43]
	v_pk_mul_f32 v[40:41], v[40:41], v[70:71]
	v_pk_mul_f32 v[42:43], v[42:43], v[72:73]
	v_cvt_pk_bf16_f32 v40, v40, v41
	v_cvt_pk_bf16_f32 v41, v42, v43
	global_store_dwordx2 v[64:65], v[40:41], off offset:96
	v_pk_mul_f32 v[44:45], v[44:45], v[68:69] op_sel_hi:[1,0]
	v_pk_mul_f32 v[46:47], v[46:47], v[68:69] op_sel_hi:[1,0]
	s_waitcnt vmcnt(15)
	v_lshlrev_b32_e32 v70, 16, v146
	v_and_b32_e32 v71, 0xffff0000, v146
	v_lshlrev_b32_e32 v72, 16, v147
	v_and_b32_e32 v73, 0xffff0000, v147
	v_pk_mul_f32 v[44:45], v[232:233], v[44:45]
	v_pk_mul_f32 v[46:47], v[234:235], v[46:47]
	v_pk_mul_f32 v[44:45], v[44:45], v[70:71]
	v_pk_mul_f32 v[46:47], v[46:47], v[72:73]
	v_cvt_pk_bf16_f32 v44, v44, v45
	v_cvt_pk_bf16_f32 v45, v46, v47
	global_store_dwordx2 v[64:65], v[44:45], off offset:112
	v_pk_mul_f32 v[16:17], v[16:17], v[68:69] op_sel_hi:[1,0]
	v_pk_mul_f32 v[18:19], v[18:19], v[68:69] op_sel_hi:[1,0]
	s_waitcnt vmcnt(15)
; DI unsigned pk2(float a, float b) { f32x2 v = {a, b}; bf2v r = __builtin_convertvector(v, bf2v); return __builtin_bit_cast(unsigned, r); }
; DI float bflo(unsigned w) { return __uint_as_float(w << 16); }
; DI float bfhi(unsigned w) { return __uint_as_float(w & 0xffff0000u); }
; template <bool SAMPLE>
; DI void gla_out(const Params& p, int item, int tbsel, LAS unsigned char* wl, int lane) {
;     ...
;         if (!SAMPLE || qi < 16) {
;             bf16_t* zr = (bf16_t*)(ws + OFF_ZB) + (size_t)(t0 + 32 * tb + qi) * 512 + h * 128 + 4 * hh;
; #pragma unroll
;             for (int dvb = 0; dvb < 4; ++dvb)
; #pragma unroll
;                 for (int g = 0; g < 4; ++g) {
;                     const int dv = 32 * dvb + 8 * g;
;                     const f32x4 gg = *(const f32x4*)(p.g_gla_out + dv + 4 * hh + lz);
;                     const u32x2 z = *(const u32x2*)(zr + dv); u32x2 w;
;                     w.x = pk2(o[dvb][4 * g] * rstd * gg[0] * bflo(z.x), o[dvb][4 * g + 1] * rstd * gg[1] * bfhi(z.x));
;                     w.y = pk2(o[dvb][4 * g + 2] * rstd * gg[2] * bflo(z.y), o[dvb][4 * g + 3] * rstd * gg[3] * bfhi(z.y));
;                     *(u32x2*)(zr + dv) = w;
;                 }
; DI void p4_gla_out(const Params& p, LAS unsigned char* lds) {
;     ...
;     for (int it = gw; it < 2048; it += NGW) gla_out<false>(p, ((it & 7) << 7) | (it >> 4), (it >> 3) & 1, wl, lane);
	v_lshlrev_b32_e32 v70, 16, v148
	v_and_b32_e32 v71, 0xffff0000, v148
	v_lshlrev_b32_e32 v72, 16, v149
	v_and_b32_e32 v73, 0xffff0000, v149
	v_pk_mul_f32 v[16:17], v[236:237], v[16:17]
	v_pk_mul_f32 v[18:19], v[238:239], v[18:19]
	v_pk_mul_f32 v[16:17], v[16:17], v[70:71]
	v_pk_mul_f32 v[18:19], v[18:19], v[72:73]
	v_cvt_pk_bf16_f32 v16, v16, v17
	v_cvt_pk_bf16_f32 v17, v18, v19
	global_store_dwordx2 v[64:65], v[16:17], off offset:128
	v_pk_mul_f32 v[20:21], v[20:21], v[68:69] op_sel_hi:[1,0]
	v_pk_mul_f32 v[22:23], v[22:23], v[68:69] op_sel_hi:[1,0]
	s_waitcnt vmcnt(15)
	v_lshlrev_b32_e32 v70, 16, v150
	v_and_b32_e32 v71, 0xffff0000, v150
	v_lshlrev_b32_e32 v72, 16, v151
	v_and_b32_e32 v73, 0xffff0000, v151
	v_pk_mul_f32 v[20:21], v[240:241], v[20:21]
	v_pk_mul_f32 v[22:23], v[242:243], v[22:23]
	v_pk_mul_f32 v[20:21], v[20:21], v[70:71]
	v_pk_mul_f32 v[22:23], v[22:23], v[72:73]
	v_cvt_pk_bf16_f32 v20, v20, v21
	v_cvt_pk_bf16_f32 v21, v22, v23
	global_store_dwordx2 v[64:65], v[20:21], off offset:144
	v_pk_mul_f32 v[24:25], v[24:25], v[68:69] op_sel_hi:[1,0]
	v_pk_mul_f32 v[26:27], v[26:27], v[68:69] op_sel_hi:[1,0]
	s_waitcnt vmcnt(15)
	v_lshlrev_b32_e32 v70, 16, v152
	v_and_b32_e32 v71, 0xffff0000, v152
	v_lshlrev_b32_e32 v72, 16, v153
	v_and_b32_e32 v73, 0xffff0000, v153
	v_pk_mul_f32 v[24:25], v[244:245], v[24:25]
	v_pk_mul_f32 v[26:27], v[246:247], v[26:27]
	v_pk_mul_f32 v[24:25], v[24:25], v[70:71]
	v_pk_mul_f32 v[26:27], v[26:27], v[72:73]
	v_cvt_pk_bf16_f32 v24, v24, v25
	v_cvt_pk_bf16_f32 v25, v26, v27
	global_store_dwordx2 v[64:65], v[24:25], off offset:160
	v_pk_mul_f32 v[28:29], v[28:29], v[68:69] op_sel_hi:[1,0]
	v_pk_mul_f32 v[30:31], v[30:31], v[68:69] op_sel_hi:[1,0]
	s_waitcnt vmcnt(15)
	v_lshlrev_b32_e32 v70, 16, v154
	v_and_b32_e32 v71, 0xffff0000, v154
	v_lshlrev_b32_e32 v72, 16, v155
	v_and_b32_e32 v73, 0xffff0000, v155
	v_pk_mul_f32 v[28:29], v[248:249], v[28:29]
	v_pk_mul_f32 v[30:31], v[250:251], v[30:31]
	v_pk_mul_f32 v[28:29], v[28:29], v[70:71]
	v_pk_mul_f32 v[30:31], v[30:31], v[72:73]
	v_cvt_pk_bf16_f32 v28, v28, v29
	v_cvt_pk_bf16_f32 v29, v30, v31
	global_store_dwordx2 v[64:65], v[28:29], off offset:176
	v_pk_mul_f32 v[0:1], v[0:1], v[68:69] op_sel_hi:[1,0]
	v_pk_mul_f32 v[2:3], v[2:3], v[68:69] op_sel_hi:[1,0]
	s_waitcnt vmcnt(15)
	v_lshlrev_b32_e32 v70, 16, v156
	v_and_b32_e32 v71, 0xffff0000, v156
	v_lshlrev_b32_e32 v72, 16, v157
	v_and_b32_e32 v73, 0xffff0000, v157
	v_pk_mul_f32 v[0:1], v[116:117], v[0:1]
	v_pk_mul_f32 v[2:3], v[118:119], v[2:3]
	v_pk_mul_f32 v[0:1], v[0:1], v[70:71]
	v_pk_mul_f32 v[2:3], v[2:3], v[72:73]
	v_cvt_pk_bf16_f32 v0, v0, v1
	v_cvt_pk_bf16_f32 v1, v2, v3
	global_store_dwordx2 v[64:65], v[0:1], off offset:192
	v_pk_mul_f32 v[4:5], v[4:5], v[68:69] op_sel_hi:[1,0]
	v_pk_mul_f32 v[6:7], v[6:7], v[68:69] op_sel_hi:[1,0]
	s_waitcnt vmcnt(15)
	v_lshlrev_b32_e32 v70, 16, v158
	v_and_b32_e32 v71, 0xffff0000, v158
	v_lshlrev_b32_e32 v72, 16, v159
	v_and_b32_e32 v73, 0xffff0000, v159
	v_pk_mul_f32 v[4:5], v[120:121], v[4:5]
	v_pk_mul_f32 v[6:7], v[122:123], v[6:7]
	v_pk_mul_f32 v[4:5], v[4:5], v[70:71]
	v_pk_mul_f32 v[6:7], v[6:7], v[72:73]
	v_cvt_pk_bf16_f32 v4, v4, v5
	v_cvt_pk_bf16_f32 v5, v6, v7
	global_store_dwordx2 v[64:65], v[4:5], off offset:208
	v_pk_mul_f32 v[8:9], v[8:9], v[68:69] op_sel_hi:[1,0]
	v_pk_mul_f32 v[10:11], v[10:11], v[68:69] op_sel_hi:[1,0]
	s_waitcnt vmcnt(15)
	v_lshlrev_b32_e32 v70, 16, v160
	v_and_b32_e32 v71, 0xffff0000, v160
	v_lshlrev_b32_e32 v72, 16, v161
	v_and_b32_e32 v73, 0xffff0000, v161
	v_pk_mul_f32 v[8:9], v[124:125], v[8:9]
	v_pk_mul_f32 v[10:11], v[126:127], v[10:11]
	v_pk_mul_f32 v[8:9], v[8:9], v[70:71]
	v_pk_mul_f32 v[10:11], v[10:11], v[72:73]
	v_cvt_pk_bf16_f32 v8, v8, v9
	v_cvt_pk_bf16_f32 v9, v10, v11
	global_store_dwordx2 v[64:65], v[8:9], off offset:224
	v_pk_mul_f32 v[12:13], v[12:13], v[68:69] op_sel_hi:[1,0]
	v_pk_mul_f32 v[14:15], v[14:15], v[68:69] op_sel_hi:[1,0]
	s_waitcnt vmcnt(15)
	v_lshlrev_b32_e32 v70, 16, v162
	v_and_b32_e32 v71, 0xffff0000, v162
	v_lshlrev_b32_e32 v72, 16, v163
	v_and_b32_e32 v73, 0xffff0000, v163
	v_pk_mul_f32 v[12:13], v[128:129], v[12:13]
	v_pk_mul_f32 v[14:15], v[130:131], v[14:15]
	v_pk_mul_f32 v[12:13], v[12:13], v[70:71]
	v_pk_mul_f32 v[14:15], v[14:15], v[72:73]
	v_cvt_pk_bf16_f32 v12, v12, v13
	v_cvt_pk_bf16_f32 v13, v14, v15
	global_store_dwordx2 v[64:65], v[12:13], off offset:240
	s_add_i32 s72, s72, s74
	s_cmpk_gt_i32 s72, 0x7ff
	s_waitcnt lgkmcnt(0)
	s_cbranch_scc1 .LBB0_1139
